# attention unit epilogue: scale and pack in registers, transpose through a per-wave LDS tile with ds_read_b64_tr_b16, 4 dwordx4 stores per lane instead of 32 short stores
# speedup vs baseline: 1.0146x; 1.0036x over previous
.LBB0_571:
	s_or_b64 exec, exec, s[10:11]
	s_ashr_i32 s10, s47, 31
	s_waitcnt lgkmcnt(0)
	s_add_u32 s11, s47, s38
	v_mov_b64_e32 v[32:33], s[26:27]
	s_addc_u32 s10, s10, 0
	s_mov_b32 s47, s39
	v_mov_b32_e32 v169, v121
	ds_read_b128 v[34:37], v139 offset:41984
	ds_read_b128 v[38:41], v139 offset:42016
	ds_read_b128 v[42:45], v139 offset:42048
	ds_read_b128 v[46:49], v139 offset:42080
	s_lshr_b32 s98, s99, 10
	s_mulk_i32 s98, 0x1200
	s_add_i32 s98, s98, 0xc000
	v_bfe_u32 v67, v191, 5, 1
	v_mul_u32_u24_e32 v66, 0x48, v118
	v_lshl_add_u32 v66, v67, 3, v66
	v_add_u32_e32 v66, s98, v66
	v_bfe_u32 v68, v191, 2, 2
	v_lshl_add_u32 v68, v67, 5, v68
	v_mul_u32_u24_e32 v68, 0x48, v68
	v_bfe_u32 v69, v191, 4, 1
	v_lshlrev_b32_e32 v69, 2, v69
	v_and_b32_e32 v70, 3, v191
	v_add_u32_e32 v69, v69, v70
	v_lshl_add_u32 v68, v69, 3, v68
	v_add_u32_e32 v68, s98, v68
	v_or_b32_e32 v70, s11, v118
	v_mad_u64_u32 v[88:89], s[28:29], v70, s57, v[32:33]
	v_mad_i32_i24 v89, s10, v137, v89
	v_lshl_add_u64 v[88:89], v[88:89], 0, s[46:47]
	v_lshl_add_u64 v[88:89], v[88:89], 0, s[44:45]
	v_lshlrev_b32_e32 v90, 6, v67
	v_mov_b32_e32 v91, v121
	v_lshl_add_u64 v[88:89], v[88:89], 0, v[90:91]
	s_waitcnt lgkmcnt(0)
	v_pk_mul_f32 v[0:1], v[0:1], v[34:35]
	v_pk_mul_f32 v[16:17], v[16:17], v[34:35]
	v_pk_mul_f32 v[2:3], v[2:3], v[36:37]
	v_pk_mul_f32 v[18:19], v[18:19], v[36:37]
	v_pk_mul_f32 v[4:5], v[4:5], v[38:39]
	v_pk_mul_f32 v[20:21], v[20:21], v[38:39]
	v_pk_mul_f32 v[6:7], v[6:7], v[40:41]
	v_pk_mul_f32 v[22:23], v[22:23], v[40:41]
	v_pk_mul_f32 v[8:9], v[8:9], v[42:43]
	v_pk_mul_f32 v[24:25], v[24:25], v[42:43]
	v_pk_mul_f32 v[10:11], v[10:11], v[44:45]
	v_pk_mul_f32 v[26:27], v[26:27], v[44:45]
	v_pk_mul_f32 v[12:13], v[12:13], v[46:47]
	v_pk_mul_f32 v[28:29], v[28:29], v[46:47]
	v_pk_mul_f32 v[14:15], v[14:15], v[48:49]
	v_pk_mul_f32 v[30:31], v[30:31], v[48:49]
	v_cvt_pk_bf16_f32 v50, v0, v1
	v_cvt_pk_bf16_f32 v58, v16, v17
	v_cvt_pk_bf16_f32 v51, v2, v3
	v_cvt_pk_bf16_f32 v59, v18, v19
	v_cvt_pk_bf16_f32 v52, v4, v5
	v_cvt_pk_bf16_f32 v60, v20, v21
	v_cvt_pk_bf16_f32 v53, v6, v7
	v_cvt_pk_bf16_f32 v61, v22, v23
	v_cvt_pk_bf16_f32 v54, v8, v9
	v_cvt_pk_bf16_f32 v62, v24, v25
	v_cvt_pk_bf16_f32 v55, v10, v11
	v_cvt_pk_bf16_f32 v63, v26, v27
	v_cvt_pk_bf16_f32 v56, v12, v13
	v_cvt_pk_bf16_f32 v64, v28, v29
	v_cvt_pk_bf16_f32 v57, v14, v15
	v_cvt_pk_bf16_f32 v65, v30, v31
	ds_write_b64 v66, v[50:51] offset:0
	ds_write_b64 v66, v[58:59] offset:2304
	ds_write_b64 v66, v[52:53] offset:16
	ds_write_b64 v66, v[60:61] offset:2320
	ds_write_b64 v66, v[54:55] offset:32
	ds_write_b64 v66, v[62:63] offset:2336
	ds_write_b64 v66, v[56:57] offset:48
	ds_write_b64 v66, v[64:65] offset:2352
	s_waitcnt lgkmcnt(0)
	ds_read_b64_tr_b16 v[72:73], v68 offset:0
	ds_read_b64_tr_b16 v[74:75], v68 offset:288
	ds_read_b64_tr_b16 v[76:77], v68 offset:576
	ds_read_b64_tr_b16 v[78:79], v68 offset:864
	ds_read_b64_tr_b16 v[80:81], v68 offset:1152
	ds_read_b64_tr_b16 v[82:83], v68 offset:1440
	ds_read_b64_tr_b16 v[84:85], v68 offset:1728
	ds_read_b64_tr_b16 v[86:87], v68 offset:2016
	s_waitcnt lgkmcnt(0)
	global_store_dwordx4 v[88:89], v[72:75], off
	global_store_dwordx4 v[88:89], v[76:79], off offset:16
	global_store_dwordx4 v[88:89], v[80:83], off offset:32
	global_store_dwordx4 v[88:89], v[84:87], off offset:48
	s_add_i32 s61, s30, s61
	s_add_i32 s53, s53, s54
	s_add_i32 s60, s60, s30
	s_cmpk_lt_i32 s61, 0x200
	s_barrier
	s_cbranch_scc0 .LBB0_636

.LBB0_604:
	s_or_b64 exec, exec, s[10:11]
	s_ashr_i32 s10, s63, 31
	s_waitcnt lgkmcnt(0)
	s_add_u32 s11, s63, s38
	v_add_u32_e32 v139, s52, v117
	v_mov_b64_e32 v[32:33], s[26:27]
	s_addc_u32 s10, s10, 0
	s_mov_b32 s47, s39
	v_mov_b32_e32 v169, v121
	ds_read_b128 v[34:37], v139 offset:41984
	ds_read_b128 v[38:41], v139 offset:42016
	ds_read_b128 v[42:45], v139 offset:42048
	ds_read_b128 v[46:49], v139 offset:42080
	s_lshr_b32 s98, s99, 10
	s_mulk_i32 s98, 0x1200
	s_add_i32 s98, s98, 0xc000
	v_bfe_u32 v67, v191, 5, 1
	v_mul_u32_u24_e32 v66, 0x48, v118
	v_lshl_add_u32 v66, v67, 3, v66
	v_add_u32_e32 v66, s98, v66
	v_bfe_u32 v68, v191, 2, 2
	v_lshl_add_u32 v68, v67, 5, v68
	v_mul_u32_u24_e32 v68, 0x48, v68
	v_bfe_u32 v69, v191, 4, 1
	v_lshlrev_b32_e32 v69, 2, v69
	v_and_b32_e32 v70, 3, v191
	v_add_u32_e32 v69, v69, v70
	v_lshl_add_u32 v68, v69, 3, v68
	v_add_u32_e32 v68, s98, v68
	v_or_b32_e32 v70, s11, v118
	v_mad_u64_u32 v[88:89], s[28:29], v70, s57, v[32:33]
	v_mad_i32_i24 v89, s10, v137, v89
	v_lshl_add_u64 v[88:89], v[88:89], 0, s[46:47]
	v_lshl_add_u64 v[88:89], v[88:89], 0, s[44:45]
	v_lshlrev_b32_e32 v90, 6, v67
	v_mov_b32_e32 v91, v121
	v_lshl_add_u64 v[88:89], v[88:89], 0, v[90:91]
	s_waitcnt lgkmcnt(0)
	v_pk_mul_f32 v[0:1], v[0:1], v[34:35]
	v_pk_mul_f32 v[16:17], v[16:17], v[34:35]
	v_pk_mul_f32 v[2:3], v[2:3], v[36:37]
	v_pk_mul_f32 v[18:19], v[18:19], v[36:37]
	v_pk_mul_f32 v[4:5], v[4:5], v[38:39]
	v_pk_mul_f32 v[20:21], v[20:21], v[38:39]
	v_pk_mul_f32 v[6:7], v[6:7], v[40:41]
	v_pk_mul_f32 v[22:23], v[22:23], v[40:41]
	v_pk_mul_f32 v[8:9], v[8:9], v[42:43]
	v_pk_mul_f32 v[24:25], v[24:25], v[42:43]
	v_pk_mul_f32 v[10:11], v[10:11], v[44:45]
	v_pk_mul_f32 v[26:27], v[26:27], v[44:45]
	v_pk_mul_f32 v[12:13], v[12:13], v[46:47]
	v_pk_mul_f32 v[28:29], v[28:29], v[46:47]
	v_pk_mul_f32 v[14:15], v[14:15], v[48:49]
	v_pk_mul_f32 v[30:31], v[30:31], v[48:49]
	v_cvt_pk_bf16_f32 v50, v0, v1
	v_cvt_pk_bf16_f32 v58, v16, v17
	v_cvt_pk_bf16_f32 v51, v2, v3
	v_cvt_pk_bf16_f32 v59, v18, v19
	v_cvt_pk_bf16_f32 v52, v4, v5
	v_cvt_pk_bf16_f32 v60, v20, v21
	v_cvt_pk_bf16_f32 v53, v6, v7
	v_cvt_pk_bf16_f32 v61, v22, v23
	v_cvt_pk_bf16_f32 v54, v8, v9
	v_cvt_pk_bf16_f32 v62, v24, v25
	v_cvt_pk_bf16_f32 v55, v10, v11
	v_cvt_pk_bf16_f32 v63, v26, v27
	v_cvt_pk_bf16_f32 v56, v12, v13
	v_cvt_pk_bf16_f32 v64, v28, v29
	v_cvt_pk_bf16_f32 v57, v14, v15
	v_cvt_pk_bf16_f32 v65, v30, v31
	ds_write_b64 v66, v[50:51] offset:0
	ds_write_b64 v66, v[58:59] offset:2304
	ds_write_b64 v66, v[52:53] offset:16
	ds_write_b64 v66, v[60:61] offset:2320
	ds_write_b64 v66, v[54:55] offset:32
	ds_write_b64 v66, v[62:63] offset:2336
	ds_write_b64 v66, v[56:57] offset:48
	ds_write_b64 v66, v[64:65] offset:2352
	s_waitcnt lgkmcnt(0)
	ds_read_b64_tr_b16 v[72:73], v68 offset:0
	ds_read_b64_tr_b16 v[74:75], v68 offset:288
	ds_read_b64_tr_b16 v[76:77], v68 offset:576
	ds_read_b64_tr_b16 v[78:79], v68 offset:864
	ds_read_b64_tr_b16 v[80:81], v68 offset:1152
	ds_read_b64_tr_b16 v[82:83], v68 offset:1440
	ds_read_b64_tr_b16 v[84:85], v68 offset:1728
	ds_read_b64_tr_b16 v[86:87], v68 offset:2016
	s_waitcnt lgkmcnt(0)
	global_store_dwordx4 v[88:89], v[72:75], off
	global_store_dwordx4 v[88:89], v[76:79], off offset:16
	global_store_dwordx4 v[88:89], v[80:83], off offset:32
	global_store_dwordx4 v[88:89], v[84:87], off offset:48
	s_sub_i32 s47, s3, s62
	s_addk_i32 s47, 0xf00
	v_or_b32_e32 v182, s47, v118
	v_ashrrev_i32_e32 v183, 31, v182
	v_lshl_add_u64 v[0:1], v[182:183], 0, s[38:39]
	v_mov_b64_e32 v[2:3], s[0:1]
	v_mad_u64_u32 v[2:3], s[10:11], v0, s55, v[2:3]
	v_mad_i32_i24 v3, v1, s55, v3
	s_mov_b32 s49, s39
	v_lshl_add_u64 v[0:1], v[2:3], 0, s[48:49]
	v_lshl_add_u64 v[0:1], v[0:1], 0, v[120:121]
	s_barrier
	global_load_dwordx4 v[80:83], v[0:1], off offset:32
	global_load_dwordx4 v[84:87], v[0:1], off offset:64
	global_load_dwordx4 v[88:91], v[0:1], off offset:96
	global_load_dwordx4 v[92:95], v[0:1], off offset:128
	global_load_dwordx4 v[96:99], v[0:1], off offset:160
	global_load_dwordx4 v[100:103], v[0:1], off
	global_load_dwordx4 v[104:107], v[178:179], off
	s_waitcnt vmcnt(40)
	v_mov_b32_e32 v108, v121
	v_mov_b32_e32 v109, v121
	v_mov_b32_e32 v110, v121
	v_mov_b32_e32 v111, v121
	s_and_saveexec_b64 s[10:11], s[4:5]
	s_cbranch_execz .LBB0_606
	v_mov_b32_e32 v177, v121
	v_lshl_add_u64 v[0:1], v[158:159], 0, v[176:177]
	global_load_dwordx4 v[108:111], v[0:1], off
